# residual-GEMM (192-row) epilogue: second half's gate/X loads hoisted to issue with the first half's, single counted vmcnt wait
# baseline (speedup 1.0000x reference)
.LBB0_1485:
	s_mul_i32 s12, s62, 0xc0
	s_add_i32 s13, s12, s56
	s_add_i32 s14, s13, 0xfffff000
	s_lshr_b32 s14, s14, 10
	v_lshl_or_b32 v114, s33, 8, v118
	s_add_i32 s14, s14, 1
	v_ashrrev_i32_e32 v115, 31, v114
	v_or_b32_e32 v116, s13, v1
	s_cmpk_gt_i32 s13, 0xfff
	v_lshlrev_b64 v[110:111], 1, v[114:115]
	v_ashrrev_i32_e32 v117, 31, v116
	v_or_b32_e32 v130, 16, v116
	s_cselect_b32 s13, s14, 0
	v_lshl_add_u64 v[112:113], s[20:21], 0, v[110:111]
	v_lshlrev_b64 v[154:155], 12, v[116:117]
	v_ashrrev_i32_e32 v131, 31, v130
	s_mul_hi_u32 s15, s13, 0x12000
	s_mul_i32 s13, s13, 0x12000
	v_lshl_add_u64 v[126:127], v[112:113], 0, v[154:155]
	v_lshlrev_b64 v[170:171], 12, v[130:131]
	s_add_u32 s14, s47, s13
	global_load_dwordx4 v[122:125], v[126:127], off
	v_lshlrev_b64 v[114:115], 2, v[114:115]
	v_lshl_add_u64 v[150:151], v[112:113], 0, v[170:171]
	s_addc_u32 s15, s52, s15
	global_load_dwordx4 v[130:133], v[150:151], off
	v_lshl_add_u64 v[146:147], s[14:15], 0, v[114:115]
	global_load_dwordx4 v[126:129], v[126:127], off offset:256
	s_nop 0
	global_load_dwordx4 v[134:137], v[146:147], off
	global_load_dwordx4 v[138:141], v[146:147], off offset:16
	global_load_dwordx4 v[142:145], v[146:147], off offset:512
	s_nop 0
	global_load_dwordx4 v[146:149], v[146:147], off offset:528
	s_nop 0
	global_load_dwordx4 v[150:153], v[150:151], off offset:256
	v_or_b32_e32 v156, 32, v116
	v_or_b32_e32 v116, 48, v116
	v_ashrrev_i32_e32 v157, 31, v156
	v_ashrrev_i32_e32 v117, 31, v116
	v_lshlrev_b64 v[172:173], 12, v[156:157]
	v_lshlrev_b64 v[116:117], 12, v[116:117]
	v_lshl_add_u64 v[154:155], s[20:21], 0, v[154:155]
	v_lshl_add_u64 v[158:159], v[112:113], 0, v[172:173]
	v_lshl_add_u64 v[166:167], v[112:113], 0, v[116:117]
	v_lshl_add_u64 v[174:175], v[154:155], 0, v[110:111]
	global_load_dwordx4 v[154:157], v[158:159], off
	s_nop 0
	global_load_dwordx4 v[158:161], v[158:159], off offset:256
	s_nop 0
	global_load_dwordx4 v[162:165], v[166:167], off
	s_nop 0
	global_load_dwordx4 v[166:169], v[166:167], off offset:256
	s_add_i32 s14, s58, s12
	s_add_i32 s12, s14, 0xfffff000
	s_lshr_b32 s12, s12, 10
	s_add_i32 s12, s12, 1
	s_cmpk_gt_i32 s14, 0xfff
	s_cselect_b32 s12, s12, 0
	s_mul_hi_u32 s13, s12, 0x12000
	s_mul_i32 s12, s12, 0x12000
	s_add_u32 s12, s47, s12
	s_addc_u32 s13, s52, s13
	s_and_b64 vcc, exec, s[48:49]
	v_or_b32_e32 v240, s14, v1
	v_ashrrev_i32_e32 v241, 31, v240
	v_lshlrev_b64 v[242:243], 12, v[240:241]
	v_lshl_add_u64 v[192:193], s[12:13], 0, v[114:115]
	v_lshl_add_u64 v[196:197], v[112:113], 0, v[242:243]
	global_load_dwordx4 v[208:211], v[192:193], off
	global_load_dwordx4 v[212:215], v[192:193], off offset:16
	global_load_dwordx4 v[216:219], v[192:193], off offset:528
	global_load_dwordx4 v[220:223], v[192:193], off offset:512
	global_load_dwordx4 v[224:227], v[196:197], off
	global_load_dwordx4 v[228:231], v[196:197], off offset:256
	v_or_b32_e32 v240, 16, v240
	v_ashrrev_i32_e32 v241, 31, v240
	v_lshlrev_b64 v[242:243], 12, v[240:241]
	v_lshl_add_u64 v[198:199], v[112:113], 0, v[242:243]
	global_load_dwordx4 v[192:195], v[198:199], off
	s_nop 0
	global_load_dwordx4 v[196:199], v[198:199], off offset:256
	s_waitcnt vmcnt(8)
	v_lshlrev_b32_e32 v176, 16, v122
	v_and_b32_e32 v177, 0xffff0000, v122
	v_lshlrev_b32_e32 v122, 16, v123
	v_and_b32_e32 v123, 0xffff0000, v123
	v_lshlrev_b32_e32 v178, 16, v124
	v_and_b32_e32 v179, 0xffff0000, v124
	v_lshlrev_b32_e32 v124, 16, v125
	v_and_b32_e32 v125, 0xffff0000, v125
	v_pk_mul_f32 v[136:137], s[24:25], v[136:137]
	v_pk_mul_f32 v[134:135], s[10:11], v[134:135]
	v_pk_mul_f32 v[140:141], s[24:25], v[140:141]
	v_pk_mul_f32 v[138:139], s[10:11], v[138:139]
	v_lshlrev_b32_e32 v180, 16, v126
	v_and_b32_e32 v181, 0xffff0000, v126
	v_lshlrev_b32_e32 v126, 16, v127
	v_and_b32_e32 v127, 0xffff0000, v127
	v_lshlrev_b32_e32 v182, 16, v128
	v_and_b32_e32 v183, 0xffff0000, v128
	v_lshlrev_b32_e32 v128, 16, v129
	v_and_b32_e32 v129, 0xffff0000, v129
	v_pk_mul_f32 v[144:145], s[24:25], v[144:145]
	v_pk_mul_f32 v[142:143], s[10:11], v[142:143]
	v_pk_mul_f32 v[148:149], s[24:25], v[148:149]
	v_pk_mul_f32 v[146:147], s[10:11], v[146:147]
	v_pk_fma_f32 v[102:103], v[102:103], v[136:137], v[122:123]
	v_pk_fma_f32 v[100:101], v[100:101], v[134:135], v[176:177]
	v_pk_fma_f32 v[98:99], v[98:99], v[140:141], v[124:125]
	v_pk_fma_f32 v[96:97], v[96:97], v[138:139], v[178:179]
	v_pk_fma_f32 v[90:91], v[90:91], v[144:145], v[126:127]
	v_pk_fma_f32 v[88:89], v[88:89], v[142:143], v[180:181]
	v_pk_fma_f32 v[122:123], v[86:87], v[148:149], v[128:129]
	v_pk_fma_f32 v[124:125], v[84:85], v[146:147], v[182:183]
	v_cvt_pk_bf16_f32 v84, v100, v101
	v_cvt_pk_bf16_f32 v85, v102, v103
	v_cvt_pk_bf16_f32 v86, v96, v97
	v_cvt_pk_bf16_f32 v87, v98, v99
	v_lshlrev_b32_e32 v186, 16, v132
	v_and_b32_e32 v187, 0xffff0000, v132
	v_cvt_pk_bf16_f32 v88, v88, v89
	v_cvt_pk_bf16_f32 v89, v90, v91
	v_cvt_pk_bf16_f32 v90, v124, v125
	v_cvt_pk_bf16_f32 v91, v122, v123
	global_store_dwordx4 v[174:175], v[84:87], off
	global_store_dwordx4 v[174:175], v[88:91], off offset:256
	v_lshlrev_b32_e32 v184, 16, v130
	v_lshlrev_b32_e32 v84, 16, v133
	v_and_b32_e32 v85, 0xffff0000, v133
	v_and_b32_e32 v185, 0xffff0000, v130
	v_lshlrev_b32_e32 v130, 16, v131
	v_and_b32_e32 v131, 0xffff0000, v131
	v_pk_fma_f32 v[84:85], v[82:83], v[140:141], v[84:85]
	v_pk_fma_f32 v[82:83], v[80:81], v[138:139], v[186:187]
	v_pk_fma_f32 v[86:87], v[94:95], v[136:137], v[130:131]
	v_pk_fma_f32 v[88:89], v[92:93], v[134:135], v[184:185]
	v_cvt_pk_bf16_f32 v82, v82, v83
	v_cvt_pk_bf16_f32 v83, v84, v85
	v_lshl_add_u64 v[84:85], s[20:21], 0, v[170:171]
	v_cvt_pk_bf16_f32 v80, v88, v89
	v_cvt_pk_bf16_f32 v81, v86, v87
	v_lshl_add_u64 v[84:85], v[84:85], 0, v[110:111]
	global_store_dwordx4 v[84:85], v[80:83], off
	v_lshlrev_b32_e32 v86, 16, v152
	v_and_b32_e32 v87, 0xffff0000, v152
	v_lshlrev_b32_e32 v80, 16, v150
	v_and_b32_e32 v81, 0xffff0000, v150
	v_lshlrev_b32_e32 v82, 16, v151
	v_and_b32_e32 v83, 0xffff0000, v151
	v_lshlrev_b32_e32 v88, 16, v153
	v_and_b32_e32 v89, 0xffff0000, v153
	v_pk_fma_f32 v[78:79], v[78:79], v[144:145], v[82:83]
	v_pk_fma_f32 v[76:77], v[76:77], v[142:143], v[80:81]
	v_pk_fma_f32 v[80:81], v[70:71], v[148:149], v[88:89]
	v_pk_fma_f32 v[70:71], v[68:69], v[146:147], v[86:87]
	v_cvt_pk_bf16_f32 v68, v76, v77
	v_cvt_pk_bf16_f32 v69, v78, v79
	v_cvt_pk_bf16_f32 v70, v70, v71
	v_cvt_pk_bf16_f32 v71, v80, v81
	global_store_dwordx4 v[84:85], v[68:71], off offset:256
	v_lshlrev_b32_e32 v76, 16, v156
	v_and_b32_e32 v77, 0xffff0000, v156
	v_lshlrev_b32_e32 v68, 16, v154
	v_and_b32_e32 v69, 0xffff0000, v154
	v_lshlrev_b32_e32 v70, 16, v155
	v_and_b32_e32 v71, 0xffff0000, v155
	v_lshlrev_b32_e32 v78, 16, v157
	v_and_b32_e32 v79, 0xffff0000, v157
	v_pk_fma_f32 v[68:69], v[72:73], v[134:135], v[68:69]
	v_pk_fma_f32 v[70:71], v[74:75], v[136:137], v[70:71]
	v_pk_fma_f32 v[72:73], v[66:67], v[140:141], v[78:79]
	v_pk_fma_f32 v[66:67], v[64:65], v[138:139], v[76:77]
	v_cvt_pk_bf16_f32 v64, v68, v69
	v_lshl_add_u64 v[68:69], s[20:21], 0, v[172:173]
	v_cvt_pk_bf16_f32 v65, v70, v71
	v_cvt_pk_bf16_f32 v66, v66, v67
	v_cvt_pk_bf16_f32 v67, v72, v73
	v_lshl_add_u64 v[68:69], v[68:69], 0, v[110:111]
	global_store_dwordx4 v[68:69], v[64:67], off
	v_lshlrev_b32_e32 v70, 16, v160
	v_and_b32_e32 v71, 0xffff0000, v160
	v_lshlrev_b32_e32 v64, 16, v158
	v_and_b32_e32 v65, 0xffff0000, v158
	v_lshlrev_b32_e32 v66, 16, v159
	v_and_b32_e32 v67, 0xffff0000, v159
	v_lshlrev_b32_e32 v72, 16, v161
	v_and_b32_e32 v73, 0xffff0000, v161
	v_pk_fma_f32 v[62:63], v[62:63], v[144:145], v[66:67]
	v_pk_fma_f32 v[60:61], v[60:61], v[142:143], v[64:65]
	v_pk_fma_f32 v[64:65], v[54:55], v[148:149], v[72:73]
	v_pk_fma_f32 v[54:55], v[52:53], v[146:147], v[70:71]
	v_cvt_pk_bf16_f32 v52, v60, v61
	v_cvt_pk_bf16_f32 v53, v62, v63
	v_cvt_pk_bf16_f32 v54, v54, v55
	v_cvt_pk_bf16_f32 v55, v64, v65
	global_store_dwordx4 v[68:69], v[52:55], off offset:256
	v_lshlrev_b32_e32 v60, 16, v164
	v_and_b32_e32 v61, 0xffff0000, v164
	v_lshlrev_b32_e32 v52, 16, v162
	v_and_b32_e32 v53, 0xffff0000, v162
	v_lshlrev_b32_e32 v54, 16, v163
	v_and_b32_e32 v55, 0xffff0000, v163
	v_lshlrev_b32_e32 v62, 16, v165
	v_and_b32_e32 v63, 0xffff0000, v165
	v_pk_fma_f32 v[52:53], v[56:57], v[134:135], v[52:53]
	v_pk_fma_f32 v[54:55], v[58:59], v[136:137], v[54:55]
	v_pk_fma_f32 v[56:57], v[50:51], v[140:141], v[62:63]
	v_pk_fma_f32 v[50:51], v[48:49], v[138:139], v[60:61]
	v_cvt_pk_bf16_f32 v48, v52, v53
	v_lshl_add_u64 v[52:53], s[20:21], 0, v[116:117]
	v_cvt_pk_bf16_f32 v49, v54, v55
	v_cvt_pk_bf16_f32 v50, v50, v51
	v_cvt_pk_bf16_f32 v51, v56, v57
	v_lshl_add_u64 v[52:53], v[52:53], 0, v[110:111]
	global_store_dwordx4 v[52:53], v[48:51], off
	v_lshlrev_b32_e32 v54, 16, v168
	v_and_b32_e32 v55, 0xffff0000, v168
	v_lshlrev_b32_e32 v48, 16, v166
	v_and_b32_e32 v49, 0xffff0000, v166
	v_lshlrev_b32_e32 v50, 16, v167
	v_and_b32_e32 v51, 0xffff0000, v167
	v_lshlrev_b32_e32 v56, 16, v169
	v_and_b32_e32 v57, 0xffff0000, v169
	v_or_b32_e32 v64, s14, v1
	v_pk_fma_f32 v[46:47], v[46:47], v[144:145], v[50:51]
	v_pk_fma_f32 v[44:45], v[44:45], v[142:143], v[48:49]
	v_pk_fma_f32 v[48:49], v[42:43], v[148:149], v[56:57]
	v_pk_fma_f32 v[42:43], v[40:41], v[146:147], v[54:55]
	v_ashrrev_i32_e32 v65, 31, v64
	v_cvt_pk_bf16_f32 v40, v44, v45
	v_cvt_pk_bf16_f32 v41, v46, v47
	v_cvt_pk_bf16_f32 v42, v42, v43
	v_cvt_pk_bf16_f32 v43, v48, v49
	v_lshlrev_b64 v[72:73], 12, v[64:65]
	global_store_dwordx4 v[52:53], v[40:43], off offset:256
	v_or_b32_e32 v64, 16, v64
	v_ashrrev_i32_e32 v65, 31, v64
	v_lshlrev_b64 v[74:75], 12, v[64:65]
	s_mov_b64 s[12:13], -1
	s_waitcnt vmcnt(8)
	v_pk_mul_f32 v[208:209], s[10:11], v[208:209]
	v_pk_mul_f32 v[210:211], s[24:25], v[210:211]
	v_pk_mul_f32 v[214:215], s[24:25], v[214:215]
	v_lshlrev_b32_e32 v76, 16, v224
	v_and_b32_e32 v77, 0xffff0000, v224
	v_pk_mul_f32 v[212:213], s[10:11], v[212:213]
	v_lshlrev_b32_e32 v224, 16, v225
	v_and_b32_e32 v225, 0xffff0000, v225
	v_lshlrev_b32_e32 v78, 16, v226
	v_and_b32_e32 v79, 0xffff0000, v226
	v_lshlrev_b32_e32 v226, 16, v227
	v_and_b32_e32 v227, 0xffff0000, v227
	v_pk_fma_f32 v[36:37], v[36:37], v[208:209], v[76:77]
	v_pk_fma_f32 v[38:39], v[38:39], v[210:211], v[224:225]
	v_pk_fma_f32 v[224:225], v[34:35], v[214:215], v[226:227]
	v_pk_fma_f32 v[34:35], v[32:33], v[212:213], v[78:79]
	v_cvt_pk_bf16_f32 v32, v36, v37
	v_lshl_add_u64 v[36:37], s[20:21], 0, v[72:73]
	v_cvt_pk_bf16_f32 v33, v38, v39
	v_cvt_pk_bf16_f32 v34, v34, v35
	v_cvt_pk_bf16_f32 v35, v224, v225
	v_lshl_add_u64 v[36:37], v[36:37], 0, v[110:111]
	v_pk_mul_f32 v[222:223], s[24:25], v[222:223]
	v_pk_mul_f32 v[220:221], s[10:11], v[220:221]
	v_pk_mul_f32 v[218:219], s[24:25], v[218:219]
	v_pk_mul_f32 v[216:217], s[10:11], v[216:217]
	global_store_dwordx4 v[36:37], v[32:35], off
	v_lshlrev_b32_e32 v38, 16, v230
	v_and_b32_e32 v39, 0xffff0000, v230
	v_lshlrev_b32_e32 v32, 16, v228
	v_and_b32_e32 v33, 0xffff0000, v228
	v_lshlrev_b32_e32 v34, 16, v229
	v_and_b32_e32 v35, 0xffff0000, v229
	v_lshlrev_b32_e32 v224, 16, v231
	v_and_b32_e32 v225, 0xffff0000, v231
	v_pk_fma_f32 v[30:31], v[30:31], v[222:223], v[34:35]
	v_pk_fma_f32 v[28:29], v[28:29], v[220:221], v[32:33]
	v_pk_fma_f32 v[32:33], v[26:27], v[218:219], v[224:225]
	v_pk_fma_f32 v[26:27], v[24:25], v[216:217], v[38:39]
	v_cvt_pk_bf16_f32 v24, v28, v29
	v_cvt_pk_bf16_f32 v25, v30, v31
	v_cvt_pk_bf16_f32 v26, v26, v27
	v_cvt_pk_bf16_f32 v27, v32, v33
	global_store_dwordx4 v[36:37], v[24:27], off offset:256
	v_lshlrev_b32_e32 v28, 16, v194
	v_and_b32_e32 v29, 0xffff0000, v194
	v_lshlrev_b32_e32 v24, 16, v192
	v_and_b32_e32 v25, 0xffff0000, v192
	v_lshlrev_b32_e32 v26, 16, v193
	v_and_b32_e32 v27, 0xffff0000, v193
	v_lshlrev_b32_e32 v30, 16, v195
	v_and_b32_e32 v31, 0xffff0000, v195
	v_pk_fma_f32 v[20:21], v[20:21], v[208:209], v[24:25]
	v_pk_fma_f32 v[22:23], v[22:23], v[210:211], v[26:27]
	v_pk_fma_f32 v[24:25], v[18:19], v[214:215], v[30:31]
	v_pk_fma_f32 v[18:19], v[16:17], v[212:213], v[28:29]
	v_cvt_pk_bf16_f32 v16, v20, v21
	v_lshl_add_u64 v[20:21], s[20:21], 0, v[74:75]
	v_cvt_pk_bf16_f32 v17, v22, v23
	v_cvt_pk_bf16_f32 v18, v18, v19
	v_cvt_pk_bf16_f32 v19, v24, v25
	v_lshl_add_u64 v[20:21], v[20:21], 0, v[110:111]
	global_store_dwordx4 v[20:21], v[16:19], off
	v_lshlrev_b32_e32 v22, 16, v198
	v_and_b32_e32 v23, 0xffff0000, v198
	v_lshlrev_b32_e32 v16, 16, v196
	v_and_b32_e32 v17, 0xffff0000, v196
	v_lshlrev_b32_e32 v18, 16, v197
	v_and_b32_e32 v19, 0xffff0000, v197
	v_lshlrev_b32_e32 v24, 16, v199
	v_and_b32_e32 v25, 0xffff0000, v199
	v_pk_fma_f32 v[14:15], v[14:15], v[222:223], v[18:19]
	v_pk_fma_f32 v[12:13], v[12:13], v[220:221], v[16:17]
	v_pk_fma_f32 v[16:17], v[10:11], v[218:219], v[24:25]
	v_pk_fma_f32 v[10:11], v[8:9], v[216:217], v[22:23]
	v_cvt_pk_bf16_f32 v8, v12, v13
	v_cvt_pk_bf16_f32 v9, v14, v15
	v_cvt_pk_bf16_f32 v10, v10, v11
	v_cvt_pk_bf16_f32 v11, v16, v17
	global_store_dwordx4 v[20:21], v[8:11], off offset:256
	s_cbranch_vccnz .LBB0_1470
	s_andn2_b64 vcc, exec, s[16:17]
	s_cbranch_vccnz .LBB0_1469
	s_barrier
	s_branch .LBB0_1469
